# K fragments: all up front in group 0 into shared registers, groups 1-2 read only the last two
# speedup vs baseline: 1.0086x; 1.0086x over previous
; #define LAS __attribute__((address_space(3)))
; #define MFMA16(a, b, c) __builtin_amdgcn_mfma_f32_16x16x32_bf16((a), (b), (c), 0, 0, 0)
; __device__ __forceinline__ void sel_group(const LAS bf16_t* Kt, const LAS bf16_t* Vt, LAS float* S, const bf16x8 qB0, const bf16x8 qB1, int jc, int rc, bool valid, bool masked, int tw64, int lr, int q) {
;     LAS float* Srow = S + (jc * 3 + rc) * 68;
;     const float mref = Srow[65]; const bool st = Srow[66] != 0.f;
;     f32x4 acc[4];
; #pragma unroll
;     for (int dt = 0; dt < 4; ++dt) acc[dt] = *(const LAS f32x4*)(Srow + 16 * dt + 4 * q);
;     float lc = Srow[64];
;     const float nm = valid ? -mref : -1e30f;
;     const f32x4 c0 = (f32x4){nm, nm, nm, nm};
;     const LAS bf16_t* kbase = Kt + lr * 72 + 8 * q;
;     f32x4 s[4];
;     {
;         bf16x8 kf[2][2];
;         kf[0][0] = *(const LAS bf16x8*)(kbase); kf[0][1] = *(const LAS bf16x8*)(kbase + 32);
; #pragma unroll
;         for (int mt = 0; mt < 4; ++mt) {
;             if (mt < 3) { kf[(mt + 1) & 1][0] = *(const LAS bf16x8*)(kbase + 16 * (mt + 1) * 72); kf[(mt + 1) & 1][1] = *(const LAS bf16x8*)(kbase + 16 * (mt + 1) * 72 + 32); }
;             __builtin_amdgcn_sched_barrier(0);
;             __builtin_amdgcn_s_setprio(1); s[mt] = MFMA16(kf[mt & 1][0], qB0, c0); s[mt] = MFMA16(kf[mt & 1][1], qB1, s[mt]); __builtin_amdgcn_s_setprio(0);
;             __builtin_amdgcn_sched_barrier(0);
;         }
;     }
;     if (masked) {
;         const int hq = tw64 + jc - 4 * q;
; #pragma unroll
;         for (int mt = 0; mt < 4; ++mt)
; #pragma unroll
;             for (int i = 0; i < 4; ++i) s[mt][i] = ((16 * mt + i) <= hq) ? s[mt][i] : -1e30f;
.Lsp_gdone_loop:
	s_waitcnt lgkmcnt(0)
	s_cmp_eq_u32 s101, 1
	s_cselect_b64 s[2:3], -1, 0
	s_cmp_eq_u32 s45, s38
	s_cselect_b64 s[12:13], -1, 0
	v_add_u32_e32 v48, s6, v99
	v_add_u32_e32 v117, v48, v97
	v_cndmask_b32_e64 v48, 0, 1, s[12:13]
	v_add3_u32 v115, s6, v104, v114
	s_cmp_eq_u32 s10, 0
	v_cmp_ne_u32_e64 s[72:73], 1, v48
	s_barrier
	s_cbranch_scc1 .LBB0_1078
	v_mad_u64_u32 v[48:49], s[4:5], v120, 3, v[88:89]
	v_mul_lo_u32 v48, v48, s36
	v_add_u32_e32 v119, s49, v48
	v_add_u32_e32 v48, v119, v97
	ds_read_b96 v[84:86], v119 offset:46336
	ds_read_b128 v[174:177], v117
	ds_read_b128 v[178:181], v117 offset:64
	ds_read_b128 v[182:185], v117 offset:2304
	ds_read_b128 v[186:189], v117 offset:2368
	ds_read_b128 v[200:203], v117 offset:4608
	ds_read_b128 v[216:219], v117 offset:4672
	ds_read_b128 v[122:125], v117 offset:6912
	ds_read_b128 v[138:141], v117 offset:6976
	ds_read_b128 v[60:63], v48 offset:46080
	ds_read_b128 v[56:59], v48 offset:46144
	ds_read_b128 v[52:55], v48 offset:46208
	ds_read_b128 v[48:51], v48 offset:46272
	s_waitcnt lgkmcnt(12)
	v_cndmask_b32_e64 v126, v222, -v85, s[76:77]
	v_mov_b32_e32 v127, v126
	v_mov_b32_e32 v128, v126
	v_mov_b32_e32 v129, v126
	s_setprio 1
	s_waitcnt lgkmcnt(11)
	v_mfma_f32_16x16x32_bf16 v[64:67], v[174:177], v[76:79], v[126:129]
	s_waitcnt lgkmcnt(10)
	v_mfma_f32_16x16x32_bf16 v[64:67], v[178:181], v[80:83], v[64:67]
	s_waitcnt lgkmcnt(9)
	v_mfma_f32_16x16x32_bf16 v[68:71], v[182:185], v[76:79], v[126:129]
	s_waitcnt lgkmcnt(8)
	v_mfma_f32_16x16x32_bf16 v[68:71], v[186:189], v[80:83], v[68:71]
	s_waitcnt lgkmcnt(7)
	v_mfma_f32_16x16x32_bf16 v[72:75], v[200:203], v[76:79], v[126:129]
	s_waitcnt lgkmcnt(6)
	v_mfma_f32_16x16x32_bf16 v[72:75], v[216:219], v[80:83], v[72:75]
	s_waitcnt lgkmcnt(5)
	v_mfma_f32_16x16x32_bf16 v[76:79], v[122:125], v[76:79], v[126:129]
	s_waitcnt lgkmcnt(4)
	v_mfma_f32_16x16x32_bf16 v[76:79], v[138:141], v[80:83], v[76:79]
	s_setprio 0
	s_and_b64 vcc, exec, s[72:73]
	s_cbranch_vccnz .LBB0_1067
	v_add_u32_e32 v80, v120, v111
	v_cmp_lt_i32_e32 vcc, -1, v80
	s_nop 1
	v_cndmask_b32_e32 v64, v222, v64, vcc
	v_cmp_lt_i32_e32 vcc, 0, v80
	s_nop 1
	v_cndmask_b32_e32 v65, v222, v65, vcc
	v_cmp_lt_i32_e32 vcc, 1, v80
	s_nop 1
	v_cndmask_b32_e32 v66, v222, v66, vcc
	v_cmp_lt_i32_e32 vcc, 2, v80
	s_nop 1
	v_cndmask_b32_e32 v67, v222, v67, vcc
	v_cmp_lt_i32_e32 vcc, 15, v80
	s_nop 1
	v_cndmask_b32_e32 v68, v222, v68, vcc
	v_cmp_lt_i32_e32 vcc, 16, v80
	s_nop 1
	v_cndmask_b32_e32 v69, v222, v69, vcc
	v_cmp_lt_i32_e32 vcc, 17, v80
	s_nop 1
	v_cndmask_b32_e32 v70, v222, v70, vcc
	v_cmp_lt_i32_e32 vcc, 18, v80
	s_nop 1
	v_cndmask_b32_e32 v71, v222, v71, vcc
	v_cmp_lt_i32_e32 vcc, 31, v80
	s_nop 1
	v_cndmask_b32_e32 v72, v222, v72, vcc
	v_cmp_lt_i32_e32 vcc, 32, v80
	s_nop 1
	v_cndmask_b32_e32 v73, v222, v73, vcc
	v_cmp_lt_i32_e32 vcc, 33, v80
	s_nop 1
	v_cndmask_b32_e32 v74, v222, v74, vcc
	v_cmp_lt_i32_e32 vcc, 34, v80
	s_nop 1
	v_cndmask_b32_e32 v75, v222, v75, vcc
	v_cmp_lt_i32_e32 vcc, 47, v80
	s_nop 1
	v_cndmask_b32_e32 v76, v222, v76, vcc
	v_cmp_lt_i32_e32 vcc, 48, v80
	s_nop 1
	v_cndmask_b32_e32 v77, v222, v77, vcc
	v_cmp_lt_i32_e32 vcc, 49, v80
	s_nop 1
	v_cndmask_b32_e32 v78, v222, v78, vcc
	v_cmp_lt_i32_e32 vcc, 50, v80
	s_nop 1
	v_cndmask_b32_e32 v79, v222, v79, vcc

; #define LAS __attribute__((address_space(3)))
; #define MFMA16(a, b, c) __builtin_amdgcn_mfma_f32_16x16x32_bf16((a), (b), (c), 0, 0, 0)
; __device__ __forceinline__ void sel_group(const LAS bf16_t* Kt, const LAS bf16_t* Vt, LAS float* S, const bf16x8 qB0, const bf16x8 qB1, int jc, int rc, bool valid, bool masked, int tw64, int lr, int q) {
;     LAS float* Srow = S + (jc * 3 + rc) * 68;
;     const float mref = Srow[65]; const bool st = Srow[66] != 0.f;
;     f32x4 acc[4];
; #pragma unroll
;     for (int dt = 0; dt < 4; ++dt) acc[dt] = *(const LAS f32x4*)(Srow + 16 * dt + 4 * q);
;     float lc = Srow[64];
;     const float nm = valid ? -mref : -1e30f;
;     const f32x4 c0 = (f32x4){nm, nm, nm, nm};
;     const LAS bf16_t* kbase = Kt + lr * 72 + 8 * q;
;     f32x4 s[4];
;     {
;         bf16x8 kf[2][2];
;         kf[0][0] = *(const LAS bf16x8*)(kbase); kf[0][1] = *(const LAS bf16x8*)(kbase + 32);
; #pragma unroll
;         for (int mt = 0; mt < 4; ++mt) {
;             if (mt < 3) { kf[(mt + 1) & 1][0] = *(const LAS bf16x8*)(kbase + 16 * (mt + 1) * 72); kf[(mt + 1) & 1][1] = *(const LAS bf16x8*)(kbase + 16 * (mt + 1) * 72 + 32); }
;             __builtin_amdgcn_sched_barrier(0);
;             __builtin_amdgcn_s_setprio(1); s[mt] = MFMA16(kf[mt & 1][0], qB0, c0); s[mt] = MFMA16(kf[mt & 1][1], qB1, s[mt]); __builtin_amdgcn_s_setprio(0);
;             __builtin_amdgcn_sched_barrier(0);
;         }
;     }
;     if (masked) {
;         const int hq = tw64 + jc - 4 * q;
; #pragma unroll
;         for (int mt = 0; mt < 4; ++mt)
; #pragma unroll
;             for (int i = 0; i < 4; ++i) s[mt][i] = ((16 * mt + i) <= hq) ? s[mt][i] : -1e30f;
.LBB0_1078:
	s_cmp_lt_u32 s10, 6
	s_cbranch_scc1 .LBB0_1092
	v_mad_u64_u32 v[48:49], s[4:5], v118, 3, v[92:93]
	v_mul_lo_u32 v48, v48, s36
	v_add_u32_e32 v79, s49, v48
	v_add_u32_e32 v48, v79, v97
	ds_read_b96 v[76:78], v79 offset:46336
	ds_read_b128 v[80:83], v117 offset:6912
	ds_read_b128 v[132:135], v117 offset:6976
	ds_read_b128 v[60:63], v48 offset:46080
	ds_read_b128 v[56:59], v48 offset:46144
	ds_read_b128 v[52:55], v48 offset:46208
	ds_read_b128 v[48:51], v48 offset:46272
	s_waitcnt lgkmcnt(6)
	v_cndmask_b32_e64 v120, v222, -v77, s[74:75]
	v_mov_b32_e32 v121, v120
	v_mov_b32_e32 v122, v120
	v_mov_b32_e32 v123, v120
	s_setprio 1
	s_nop 0
	v_mfma_f32_16x16x32_bf16 v[64:67], v[174:177], v[40:43], v[120:123]
	v_mfma_f32_16x16x32_bf16 v[64:67], v[178:181], v[44:47], v[64:67]
	v_mfma_f32_16x16x32_bf16 v[68:71], v[182:185], v[40:43], v[120:123]
	v_mfma_f32_16x16x32_bf16 v[68:71], v[186:189], v[44:47], v[68:71]
	v_mfma_f32_16x16x32_bf16 v[72:75], v[200:203], v[40:43], v[120:123]
	v_mfma_f32_16x16x32_bf16 v[72:75], v[216:219], v[44:47], v[72:75]
	s_waitcnt lgkmcnt(5)
	v_mfma_f32_16x16x32_bf16 v[40:43], v[80:83], v[40:43], v[120:123]
	s_waitcnt lgkmcnt(4)
	v_mfma_f32_16x16x32_bf16 v[40:43], v[132:135], v[44:47], v[40:43]
	s_setprio 0
	s_and_b64 vcc, exec, s[72:73]
	s_cbranch_vccnz .LBB0_1081
	v_add_u32_e32 v44, v118, v111
	v_cmp_lt_i32_e32 vcc, -1, v44
	s_nop 1
	v_cndmask_b32_e32 v64, v222, v64, vcc
	v_cmp_lt_i32_e32 vcc, 0, v44
	s_nop 1
	v_cndmask_b32_e32 v65, v222, v65, vcc
	v_cmp_lt_i32_e32 vcc, 1, v44
	s_nop 1
	v_cndmask_b32_e32 v66, v222, v66, vcc
	v_cmp_lt_i32_e32 vcc, 2, v44
	s_nop 1
	v_cndmask_b32_e32 v67, v222, v67, vcc
	v_cmp_lt_i32_e32 vcc, 15, v44
	s_nop 1
	v_cndmask_b32_e32 v68, v222, v68, vcc
	v_cmp_lt_i32_e32 vcc, 16, v44
	s_nop 1
	v_cndmask_b32_e32 v69, v222, v69, vcc
	v_cmp_lt_i32_e32 vcc, 17, v44
	s_nop 1
	v_cndmask_b32_e32 v70, v222, v70, vcc
	v_cmp_lt_i32_e32 vcc, 18, v44
	s_nop 1
	v_cndmask_b32_e32 v71, v222, v71, vcc
	v_cmp_lt_i32_e32 vcc, 31, v44
	s_nop 1
	v_cndmask_b32_e32 v72, v222, v72, vcc
	v_cmp_lt_i32_e32 vcc, 32, v44
	s_nop 1
	v_cndmask_b32_e32 v73, v222, v73, vcc
	v_cmp_lt_i32_e32 vcc, 33, v44
	s_nop 1
	v_cndmask_b32_e32 v74, v222, v74, vcc
	v_cmp_lt_i32_e32 vcc, 34, v44
	s_nop 1
	v_cndmask_b32_e32 v75, v222, v75, vcc
	v_cmp_lt_i32_e32 vcc, 47, v44
	s_nop 1
	v_cndmask_b32_e32 v40, v222, v40, vcc
	v_cmp_lt_i32_e32 vcc, 48, v44
	s_nop 1
	v_cndmask_b32_e32 v41, v222, v41, vcc
	v_cmp_lt_i32_e32 vcc, 49, v44
	s_nop 1
	v_cndmask_b32_e32 v42, v222, v42, vcc
	v_cmp_lt_i32_e32 vcc, 50, v44
	s_nop 1
	v_cndmask_b32_e32 v43, v222, v43, vcc

; #define LAS __attribute__((address_space(3)))
; #define MFMA16(a, b, c) __builtin_amdgcn_mfma_f32_16x16x32_bf16((a), (b), (c), 0, 0, 0)
; __device__ __forceinline__ void sel_group(const LAS bf16_t* Kt, const LAS bf16_t* Vt, LAS float* S, const bf16x8 qB0, const bf16x8 qB1, int jc, int rc, bool valid, bool masked, int tw64, int lr, int q) {
;     LAS float* Srow = S + (jc * 3 + rc) * 68;
;     const float mref = Srow[65]; const bool st = Srow[66] != 0.f;
;     f32x4 acc[4];
; #pragma unroll
;     for (int dt = 0; dt < 4; ++dt) acc[dt] = *(const LAS f32x4*)(Srow + 16 * dt + 4 * q);
;     float lc = Srow[64];
;     const float nm = valid ? -mref : -1e30f;
;     const f32x4 c0 = (f32x4){nm, nm, nm, nm};
;     const LAS bf16_t* kbase = Kt + lr * 72 + 8 * q;
;     f32x4 s[4];
;     {
;         bf16x8 kf[2][2];
;         kf[0][0] = *(const LAS bf16x8*)(kbase); kf[0][1] = *(const LAS bf16x8*)(kbase + 32);
; #pragma unroll
;         for (int mt = 0; mt < 4; ++mt) {
;             if (mt < 3) { kf[(mt + 1) & 1][0] = *(const LAS bf16x8*)(kbase + 16 * (mt + 1) * 72); kf[(mt + 1) & 1][1] = *(const LAS bf16x8*)(kbase + 16 * (mt + 1) * 72 + 32); }
;             __builtin_amdgcn_sched_barrier(0);
;             __builtin_amdgcn_s_setprio(1); s[mt] = MFMA16(kf[mt & 1][0], qB0, c0); s[mt] = MFMA16(kf[mt & 1][1], qB1, s[mt]); __builtin_amdgcn_s_setprio(0);
;             __builtin_amdgcn_sched_barrier(0);
;         }
;     }
;     if (masked) {
;         const int hq = tw64 + jc - 4 * q;
; #pragma unroll
;         for (int mt = 0; mt < 4; ++mt)
; #pragma unroll
;             for (int i = 0; i < 4; ++i) s[mt][i] = ((16 * mt + i) <= hq) ? s[mt][i] : -1e30f;
.LBB0_1092:
	s_cmp_lt_u32 s10, 11
	s_cbranch_scc1 .LBB0_1057
	s_nop 0
	v_mad_u64_u32 v[40:41], s[4:5], v116, 3, v[96:97]
	v_mul_lo_u32 v40, v40, s36
	v_add_u32_e32 v71, s49, v40
	v_add_u32_e32 v40, v71, v97
	ds_read_b96 v[68:70], v71 offset:46336
	ds_read_b128 v[72:75], v117 offset:6912
	ds_read_b128 v[122:125], v117 offset:6976
	ds_read_b128 v[52:55], v40 offset:46080
	ds_read_b128 v[48:51], v40 offset:46144
	ds_read_b128 v[44:47], v40 offset:46208
	ds_read_b128 v[40:43], v40 offset:46272
	s_waitcnt lgkmcnt(6)
	v_cndmask_b32_e64 v76, v222, -v69, s[70:71]
	v_mov_b32_e32 v77, v76
	v_mov_b32_e32 v78, v76
	v_mov_b32_e32 v79, v76
	s_setprio 1
	s_nop 0
	v_mfma_f32_16x16x32_bf16 v[56:59], v[174:177], v[32:35], v[76:79]
	v_mfma_f32_16x16x32_bf16 v[56:59], v[178:181], v[36:39], v[56:59]
	v_mfma_f32_16x16x32_bf16 v[60:63], v[182:185], v[32:35], v[76:79]
	v_mfma_f32_16x16x32_bf16 v[60:63], v[186:189], v[36:39], v[60:63]
	v_mfma_f32_16x16x32_bf16 v[64:67], v[200:203], v[32:35], v[76:79]
	v_mfma_f32_16x16x32_bf16 v[64:67], v[216:219], v[36:39], v[64:67]
	s_waitcnt lgkmcnt(5)
	v_mfma_f32_16x16x32_bf16 v[32:35], v[72:75], v[32:35], v[76:79]
	s_waitcnt lgkmcnt(4)
	v_mfma_f32_16x16x32_bf16 v[32:35], v[122:125], v[36:39], v[32:35]
	s_setprio 0
	s_and_b64 vcc, exec, s[72:73]
	s_cbranch_vccnz .LBB0_1095
	v_add_u32_e32 v36, v116, v111
	v_cmp_lt_i32_e32 vcc, -1, v36
	s_nop 1
	v_cndmask_b32_e32 v56, v222, v56, vcc
	v_cmp_lt_i32_e32 vcc, 0, v36
	s_nop 1
	v_cndmask_b32_e32 v57, v222, v57, vcc
	v_cmp_lt_i32_e32 vcc, 1, v36
	s_nop 1
	v_cndmask_b32_e32 v58, v222, v58, vcc
	v_cmp_lt_i32_e32 vcc, 2, v36
	s_nop 1
	v_cndmask_b32_e32 v59, v222, v59, vcc
	v_cmp_lt_i32_e32 vcc, 15, v36
	s_nop 1
	v_cndmask_b32_e32 v60, v222, v60, vcc
	v_cmp_lt_i32_e32 vcc, 16, v36
	s_nop 1
	v_cndmask_b32_e32 v61, v222, v61, vcc
	v_cmp_lt_i32_e32 vcc, 17, v36
	s_nop 1
	v_cndmask_b32_e32 v62, v222, v62, vcc
	v_cmp_lt_i32_e32 vcc, 18, v36
	s_nop 1
	v_cndmask_b32_e32 v63, v222, v63, vcc
	v_cmp_lt_i32_e32 vcc, 31, v36
	s_nop 1
	v_cndmask_b32_e32 v64, v222, v64, vcc
	v_cmp_lt_i32_e32 vcc, 32, v36
	s_nop 1
	v_cndmask_b32_e32 v65, v222, v65, vcc
	v_cmp_lt_i32_e32 vcc, 33, v36
	s_nop 1
	v_cndmask_b32_e32 v66, v222, v66, vcc
	v_cmp_lt_i32_e32 vcc, 34, v36
	s_nop 1
	v_cndmask_b32_e32 v67, v222, v67, vcc
	v_cmp_lt_i32_e32 vcc, 47, v36
	s_nop 1
	v_cndmask_b32_e32 v32, v222, v32, vcc
	v_cmp_lt_i32_e32 vcc, 48, v36
	s_nop 1
	v_cndmask_b32_e32 v33, v222, v33, vcc
	v_cmp_lt_i32_e32 vcc, 49, v36
	s_nop 1
	v_cndmask_b32_e32 v34, v222, v34, vcc
	v_cmp_lt_i32_e32 vcc, 50, v36
	s_nop 1
	v_cndmask_b32_e32 v35, v222, v35, vcc
